# v23 + all attention-loop work reductions stacked: q-gain hoist with late next-Q wait, fmamk exp2 argument, nt on Q/K/V loads
# speedup vs baseline: 1.0024x; 1.0024x over previous
; __device__ __forceinline__ unsigned pk2(float lo, float hi) { f32x2_t v = {lo, hi}; bf16x2_t b = __builtin_convertvector(v, bf16x2_t); return __builtin_bit_cast(unsigned, b); }
; #define LDS_WAIT() asm volatile("s_waitcnt lgkmcnt(0)" ::: "memory")
; __device__ __forceinline__ void attn_unit(const AtArgs& A, unsigned char* lds, int unit, int tid, int wave, int lane) {
;     ...
;         const int q0 = qh * 64 + st * 16;
;         {
;             const int row = lane >> 2, chunk = lane & 3;
;             const size_t t = (size_t)b * SEQ + nb * 128 + q0 + row;
;             float x[16];
;             const u32x4 qc0 = qn0, qc1 = qn1;
;             { const bf16* pn = pq0 + (size_t)((st < 3) ? st + 1 : 3) * 16 * QW; qn0 = *(const u32x4*)pn; qn1 = *(const u32x4*)(pn + 8); }
;             norm_rope(qc0, qc1, A.qg, chunk, ROPE + t * 16, 0.125f, x);
;             u32x4 o0, o1; o0.x = pk2(x[0], x[1]); o0.y = pk2(x[2], x[3]); o0.z = pk2(x[4], x[5]); o0.w = pk2(x[6], x[7]); o1.x = pk2(x[8], x[9]); o1.y = pk2(x[10], x[11]); o1.z = pk2(x[12], x[13]); o1.w = pk2(x[14], x[15]);
;             *(u32x4*)(QS + row * QST + chunk * 16) = o0; *(u32x4*)(QS + row * QST + chunk * 16 + 8) = o1;
;         }
;         LDS_WAIT();
;         const bf16x8 qa0 = *(const bf16x8*)(QS + fr * QST + fq * 8), qa1 = *(const bf16x8*)(QS + fr * QST + 32 + fq * 8);
;         f32x4 sc[9];
; #pragma unroll
;         for (int kt = 0; kt < 9; ++kt) {
;             const int key = (q0 / 16 + kt) * 16 + fr;
;             const bf16x8 kb0 = *(const bf16x8*)(KS + key * KST + fq * 8), kb1 = *(const bf16x8*)(KS + key * KST + 32 + fq * 8);
;             f32x4 a = (f32x4){0.f, 0.f, 0.f, 0.f};
;             a = __builtin_amdgcn_mfma_f32_16x16x32_bf16(qa0, kb0, a, 0, 0, 0); a = __builtin_amdgcn_mfma_f32_16x16x32_bf16(qa1, kb1, a, 0, 0, 0);
; #pragma unroll
;             for (int r = 0; r < 4; ++r) {
;                 const int qi = q0 + fq * 4 + r;
;                 const bool ok = (key > qi) && (key <= qi + 128) && (nb > 0 || key >= 128);
;                 a[r] = ok ? a[r] : -1e30f;
;             }
;             sc[kt] = a;
;         }
.LBB0_510:
	s_or_b64 exec, exec, s[0:1]
	s_cmp_lg_u32 s2, 48
	s_cselect_b32 s6, s3, 0x21000
	v_lshl_add_u64 v[4:5], s[6:7], 1, v[50:51]
	global_load_dwordx4 v[0:3], v[4:5], off offset:16 nt
	s_nop 0
	global_load_dwordx4 v[4:7], v[4:5], off nt
	s_nop 0
	v_pk_mul_f32 v[18:19], v[60:61], s[14:15] op_sel_hi:[1,0]
	v_pk_mul_f32 v[20:21], v[28:29], s[14:15] op_sel_hi:[1,0]
	v_pk_mul_f32 v[22:23], v[24:25], s[14:15] op_sel_hi:[1,0]
	v_pk_mul_f32 v[12:13], v[12:13], s[14:15] op_sel_hi:[1,0]
	v_pk_mul_f32 v[24:25], v[8:9], s[14:15] op_sel_hi:[1,0]
	v_pk_mul_f32 v[26:27], v[10:11], s[14:15] op_sel_hi:[1,0]
	v_pk_mul_f32 v[14:15], v[14:15], s[14:15] op_sel_hi:[1,0]
	v_pk_mul_f32 v[16:17], v[16:17], s[14:15] op_sel_hi:[1,0]
	v_cvt_pk_bf16_f32 v8, v18, v19
	v_cvt_pk_bf16_f32 v9, v20, v21
	v_cvt_pk_bf16_f32 v10, v22, v23
	v_cvt_pk_bf16_f32 v11, v12, v13
	v_cvt_pk_bf16_f32 v12, v24, v25
	v_cvt_pk_bf16_f32 v13, v26, v27
	v_cvt_pk_bf16_f32 v14, v14, v15
	v_cvt_pk_bf16_f32 v15, v16, v17
	ds_write_b128 v75, v[8:11]
	ds_write_b128 v75, v[12:15] offset:16
	s_waitcnt lgkmcnt(0)
	ds_read_b128 v[12:15], v76
	ds_read_b128 v[8:11], v76 offset:64
	ds_read_b128 v[16:19], v95
	ds_read_b128 v[20:23], v95 offset:64
	s_waitcnt lgkmcnt(1)
	v_mfma_f32_16x16x32_bf16 v[16:19], v[12:15], v[16:19], 0
	v_add_u32_e32 v30, s2, v85
	v_add_u32_e32 v31, s2, v88
	v_add_u32_e32 v58, 1, v31
	s_waitcnt lgkmcnt(0)
	v_mfma_f32_16x16x32_bf16 v[16:19], v[8:11], v[20:23], v[16:19]
	v_add_u32_e32 v20, 0xffffff80, v30
	v_cmp_ge_i32_e32 vcc, v31, v20
	s_and_b64 s[0:1], s[42:43], vcc
	s_and_b64 vcc, s[16:17], s[0:1]
	v_cmp_ge_i32_e64 s[0:1], v58, v20
	s_nop 2
	v_cndmask_b32_e32 v29, v93, v16, vcc
	v_cmp_gt_i32_e32 vcc, v30, v58
	s_and_b64 s[0:1], vcc, s[0:1]
	s_and_b64 vcc, s[16:17], s[0:1]
	v_add_u32_e32 v59, 2, v31
	ds_read_b128 v[96:99], v95 offset:2304
	ds_read_b128 v[100:103], v95 offset:2368
	v_cndmask_b32_e32 v22, v93, v17, vcc
	v_cmp_gt_i32_e32 vcc, v30, v59
	v_cmp_ge_i32_e64 s[0:1], v59, v20
	s_and_b64 s[0:1], vcc, s[0:1]
	s_and_b64 vcc, s[16:17], s[0:1]
	v_add_u32_e32 v60, 3, v31
	v_cndmask_b32_e32 v18, v93, v18, vcc
	v_cmp_gt_i32_e32 vcc, v30, v60
	v_cmp_ge_i32_e64 s[0:1], v60, v20
	s_waitcnt lgkmcnt(1)
	v_mfma_f32_16x16x32_bf16 v[96:99], v[12:15], v[96:99], 0
	s_and_b64 s[0:1], vcc, s[0:1]
	s_add_i32 s6, s4, s2
	s_and_b64 vcc, s[16:17], s[0:1]
	s_add_i32 s0, s6, 16
	s_cmpk_gt_u32 s0, 0x7f
	v_cndmask_b32_e32 v16, v93, v19, vcc
	v_add_u32_e32 v17, 16, v30
	s_waitcnt lgkmcnt(0)
	v_mfma_f32_16x16x32_bf16 v[96:99], v[8:11], v[100:103], v[96:99]
	v_add_u32_e32 v19, 0xffffff90, v30
	s_cselect_b64 s[0:1], -1, 0
	s_or_b64 s[10:11], s[16:17], s[0:1]
	v_cmp_gt_i32_e32 vcc, v17, v31
	v_cmp_ge_i32_e64 s[0:1], v31, v19
	s_and_b64 s[0:1], vcc, s[0:1]
	s_and_b64 vcc, s[0:1], s[10:11]
	s_nop 0
	v_cndmask_b32_e32 v96, v93, v96, vcc
	v_cmp_gt_i32_e32 vcc, v17, v58
	v_cmp_ge_i32_e64 s[0:1], v58, v19
	s_and_b64 s[0:1], vcc, s[0:1]
	s_and_b64 vcc, s[0:1], s[10:11]
	v_cndmask_b32_e32 v26, v93, v97, vcc
	v_cmp_gt_i32_e32 vcc, v17, v59
	v_cmp_ge_i32_e64 s[0:1], v59, v19
	s_and_b64 s[0:1], vcc, s[0:1]
	s_and_b64 vcc, s[0:1], s[10:11]
	v_cndmask_b32_e32 v20, v93, v98, vcc
	v_cmp_gt_i32_e32 vcc, v17, v60
	v_cmp_ge_i32_e64 s[0:1], v60, v19
	s_and_b64 s[0:1], vcc, s[0:1]
	s_and_b64 vcc, s[0:1], s[10:11]
	v_cndmask_b32_e32 v17, v93, v99, vcc
	ds_read_b128 v[98:101], v95 offset:4608
	ds_read_b128 v[108:111], v95 offset:4672
	s_waitcnt lgkmcnt(1)
	v_mfma_f32_16x16x32_bf16 v[98:101], v[12:15], v[98:101], 0
	s_add_i32 s0, s6, 32
	s_cmpk_gt_u32 s0, 0x7f
	v_add_u32_e32 v19, 32, v30
	s_waitcnt lgkmcnt(0)
	v_mfma_f32_16x16x32_bf16 v[100:103], v[8:11], v[108:111], v[98:101]
	v_add_u32_e32 v21, 0xffffffa0, v30
	s_cselect_b64 s[0:1], -1, 0
	s_or_b64 s[10:11], s[16:17], s[0:1]
	v_cmp_gt_i32_e32 vcc, v19, v31
	v_cmp_ge_i32_e64 s[0:1], v31, v21
	s_and_b64 s[0:1], vcc, s[0:1]
	s_and_b64 vcc, s[0:1], s[10:11]
	s_nop 0
	v_cndmask_b32_e32 v100, v93, v100, vcc
	v_cmp_gt_i32_e32 vcc, v19, v58
	v_cmp_ge_i32_e64 s[0:1], v58, v21
	s_and_b64 s[0:1], vcc, s[0:1]
	s_and_b64 vcc, s[0:1], s[10:11]
	ds_read_b128 v[108:111], v95 offset:6912
	ds_read_b128 v[112:115], v95 offset:6976
	v_cndmask_b32_e32 v56, v93, v101, vcc
	v_cmp_gt_i32_e32 vcc, v19, v59
	v_cmp_ge_i32_e64 s[0:1], v59, v21
	s_and_b64 s[0:1], vcc, s[0:1]
	s_and_b64 vcc, s[0:1], s[10:11]
	v_cndmask_b32_e32 v23, v93, v102, vcc
	v_cmp_gt_i32_e32 vcc, v19, v60
	v_cmp_ge_i32_e64 s[0:1], v60, v21
	s_waitcnt lgkmcnt(1)
	v_mfma_f32_16x16x32_bf16 v[108:111], v[12:15], v[108:111], 0
	s_and_b64 s[0:1], vcc, s[0:1]
	s_and_b64 vcc, s[0:1], s[10:11]
	s_add_i32 s0, s6, 48
	s_cmpk_gt_u32 s0, 0x7f
	v_add_u32_e32 v21, 48, v30
	s_waitcnt lgkmcnt(0)
	v_mfma_f32_16x16x32_bf16 v[108:111], v[8:11], v[112:115], v[108:111]
	v_add_u32_e32 v25, 0xffffffb0, v30
	s_cselect_b64 s[0:1], -1, 0
	v_cndmask_b32_e32 v19, v93, v103, vcc
	s_or_b64 s[10:11], s[16:17], s[0:1]
	v_cmp_gt_i32_e32 vcc, v21, v31
	v_cmp_ge_i32_e64 s[0:1], v31, v25
	s_and_b64 s[0:1], vcc, s[0:1]
	s_and_b64 vcc, s[0:1], s[10:11]
	v_cndmask_b32_e32 v103, v93, v108, vcc
	v_cmp_gt_i32_e32 vcc, v21, v58
	v_cmp_ge_i32_e64 s[0:1], v58, v25
	s_and_b64 s[0:1], vcc, s[0:1]
	s_and_b64 vcc, s[0:1], s[10:11]
	v_cndmask_b32_e32 v97, v93, v109, vcc
	v_cmp_gt_i32_e32 vcc, v21, v59
	v_cmp_ge_i32_e64 s[0:1], v59, v25
	s_and_b64 s[0:1], vcc, s[0:1]
	s_and_b64 vcc, s[0:1], s[10:11]
	v_cndmask_b32_e32 v27, v93, v110, vcc
	v_cmp_gt_i32_e32 vcc, v21, v60
	v_cmp_ge_i32_e64 s[0:1], v60, v25
	s_and_b64 s[0:1], vcc, s[0:1]
	s_and_b64 vcc, s[0:1], s[10:11]
	v_cndmask_b32_e32 v21, v93, v111, vcc
	ds_read_b128 v[108:111], v95 offset:9216
	ds_read_b128 v[112:115], v95 offset:9280
	s_waitcnt lgkmcnt(1)
; __device__ __forceinline__ void attn_unit(const AtArgs& A, unsigned char* lds, int unit, int tid, int wave, int lane) {
;     ...
;         for (int kt = 0; kt < 9; ++kt) {
;             const int key = (q0 / 16 + kt) * 16 + fr;
;             const bf16x8 kb0 = *(const bf16x8*)(KS + key * KST + fq * 8), kb1 = *(const bf16x8*)(KS + key * KST + 32 + fq * 8);
;             f32x4 a = (f32x4){0.f, 0.f, 0.f, 0.f};
;             a = __builtin_amdgcn_mfma_f32_16x16x32_bf16(qa0, kb0, a, 0, 0, 0); a = __builtin_amdgcn_mfma_f32_16x16x32_bf16(qa1, kb1, a, 0, 0, 0);
; #pragma unroll
;             for (int r = 0; r < 4; ++r) {
;                 const int qi = q0 + fq * 4 + r;
;                 const bool ok = (key > qi) && (key <= qi + 128) && (nb > 0 || key >= 128);
;                 a[r] = ok ? a[r] : -1e30f;
;             }
;             sc[kt] = a;
;         }
	v_mfma_f32_16x16x32_bf16 v[108:111], v[12:15], v[108:111], 0
	s_add_i32 s0, s6, 64
	s_cmpk_gt_u32 s0, 0x7f
	v_add_u32_e32 v25, 64, v30
	s_waitcnt lgkmcnt(0)
	v_mfma_f32_16x16x32_bf16 v[108:111], v[8:11], v[112:115], v[108:111]
	v_subrev_u32_e32 v28, 64, v30
	s_cselect_b64 s[0:1], -1, 0
	s_or_b64 s[10:11], s[16:17], s[0:1]
	v_cmp_gt_i32_e32 vcc, v25, v31
	v_cmp_ge_i32_e64 s[0:1], v31, v28
	s_and_b64 s[0:1], vcc, s[0:1]
	s_and_b64 vcc, s[0:1], s[10:11]
	s_nop 0
	v_cndmask_b32_e32 v116, v93, v108, vcc
	v_cmp_gt_i32_e32 vcc, v25, v58
	v_cmp_ge_i32_e64 s[0:1], v58, v28
	s_and_b64 s[0:1], vcc, s[0:1]
	s_and_b64 vcc, s[0:1], s[10:11]
	v_cndmask_b32_e32 v101, v93, v109, vcc
	v_cmp_gt_i32_e32 vcc, v25, v59
	v_cmp_ge_i32_e64 s[0:1], v59, v28
	s_and_b64 s[0:1], vcc, s[0:1]
	s_and_b64 vcc, s[0:1], s[10:11]
	v_cndmask_b32_e32 v57, v93, v110, vcc
	v_cmp_gt_i32_e32 vcc, v25, v60
	v_cmp_ge_i32_e64 s[0:1], v60, v28
	s_and_b64 s[0:1], vcc, s[0:1]
	s_and_b64 vcc, s[0:1], s[10:11]
	v_cndmask_b32_e32 v25, v93, v111, vcc
	ds_read_b128 v[108:111], v95 offset:11520
	ds_read_b128 v[112:115], v95 offset:11584
	s_waitcnt lgkmcnt(1)
	v_mfma_f32_16x16x32_bf16 v[108:111], v[12:15], v[108:111], 0
	s_add_i32 s0, s6, 0x50
	s_cmpk_gt_u32 s0, 0x7f
	v_add_u32_e32 v28, 0x50, v30
	s_waitcnt lgkmcnt(0)
	v_mfma_f32_16x16x32_bf16 v[108:111], v[8:11], v[112:115], v[108:111]
	v_subrev_u32_e32 v61, 48, v30
	s_cselect_b64 s[0:1], -1, 0
	s_or_b64 s[10:11], s[16:17], s[0:1]
	v_cmp_gt_i32_e32 vcc, v28, v31
	v_cmp_ge_i32_e64 s[0:1], v31, v61
	s_and_b64 s[0:1], vcc, s[0:1]
	s_and_b64 vcc, s[0:1], s[10:11]
	s_nop 0
	v_cndmask_b32_e32 v117, v93, v108, vcc
	v_cmp_gt_i32_e32 vcc, v28, v58
	v_cmp_ge_i32_e64 s[0:1], v58, v61
	s_and_b64 s[0:1], vcc, s[0:1]
	s_and_b64 vcc, s[0:1], s[10:11]
	v_cndmask_b32_e32 v118, v93, v109, vcc
	v_cmp_gt_i32_e32 vcc, v28, v59
	v_cmp_ge_i32_e64 s[0:1], v59, v61
	s_and_b64 s[0:1], vcc, s[0:1]
	s_and_b64 vcc, s[0:1], s[10:11]
	v_cndmask_b32_e32 v98, v93, v110, vcc
	v_cmp_gt_i32_e32 vcc, v28, v60
	v_cmp_ge_i32_e64 s[0:1], v60, v61
	s_and_b64 s[0:1], vcc, s[0:1]
	s_and_b64 vcc, s[0:1], s[10:11]
	v_cndmask_b32_e32 v28, v93, v111, vcc
	ds_read_b128 v[108:111], v95 offset:13824
	ds_read_b128 v[112:115], v95 offset:13888
	s_waitcnt lgkmcnt(1)
	v_mfma_f32_16x16x32_bf16 v[108:111], v[12:15], v[108:111], 0
	s_add_i32 s0, s6, 0x60
	s_cmpk_gt_u32 s0, 0x7f
	v_add_u32_e32 v61, 0x60, v30
	s_waitcnt lgkmcnt(0)
	v_mfma_f32_16x16x32_bf16 v[108:111], v[8:11], v[112:115], v[108:111]
	v_subrev_u32_e32 v99, 32, v30
	s_cselect_b64 s[0:1], -1, 0
	s_or_b64 s[10:11], s[16:17], s[0:1]
	v_cmp_gt_i32_e32 vcc, v61, v31
	v_cmp_ge_i32_e64 s[0:1], v31, v99
	s_and_b64 s[0:1], vcc, s[0:1]
	s_and_b64 vcc, s[0:1], s[10:11]
	s_nop 0
	v_cndmask_b32_e32 v119, v93, v108, vcc
	v_cmp_gt_i32_e32 vcc, v61, v58
	v_cmp_ge_i32_e64 s[0:1], v58, v99
	s_and_b64 s[0:1], vcc, s[0:1]
	s_and_b64 vcc, s[0:1], s[10:11]
	v_cndmask_b32_e32 v120, v93, v109, vcc
	v_cmp_gt_i32_e32 vcc, v61, v59
	v_cmp_ge_i32_e64 s[0:1], v59, v99
	s_and_b64 s[0:1], vcc, s[0:1]
	s_and_b64 vcc, s[0:1], s[10:11]
	v_cndmask_b32_e32 v102, v93, v110, vcc
	v_cmp_gt_i32_e32 vcc, v61, v60
	v_cmp_ge_i32_e64 s[0:1], v60, v99
	s_and_b64 s[0:1], vcc, s[0:1]
	s_and_b64 vcc, s[0:1], s[10:11]
	v_cndmask_b32_e32 v61, v93, v111, vcc
	ds_read_b128 v[108:111], v95 offset:16128
	ds_read_b128 v[112:115], v95 offset:16192
	s_waitcnt lgkmcnt(1)
	v_mfma_f32_16x16x32_bf16 v[108:111], v[12:15], v[108:111], 0
	s_addk_i32 s6, 0x70
	s_cmpk_gt_u32 s6, 0x7f
	v_add_u32_e32 v99, 0x70, v30
	s_waitcnt lgkmcnt(0)
	v_mfma_f32_16x16x32_bf16 v[108:111], v[8:11], v[112:115], v[108:111]
	v_add_u32_e32 v112, -16, v30
	s_cselect_b64 s[0:1], -1, 0
	s_or_b64 s[10:11], s[16:17], s[0:1]
	v_cmp_gt_i32_e32 vcc, v99, v31
	v_cmp_ge_i32_e64 s[0:1], v31, v112
	s_and_b64 s[0:1], vcc, s[0:1]
	s_and_b64 vcc, s[0:1], s[10:11]
	s_nop 0
	v_cndmask_b32_e32 v121, v93, v108, vcc
	v_cmp_gt_i32_e32 vcc, v99, v58
	v_cmp_ge_i32_e64 s[0:1], v58, v112
	s_and_b64 s[0:1], vcc, s[0:1]
	s_and_b64 vcc, s[0:1], s[10:11]
	v_cndmask_b32_e32 v122, v93, v109, vcc
	v_cmp_gt_i32_e32 vcc, v99, v59
	v_cmp_ge_i32_e64 s[0:1], v59, v112
	s_and_b64 s[0:1], vcc, s[0:1]
	s_and_b64 vcc, s[0:1], s[10:11]
	v_cndmask_b32_e32 v123, v93, v110, vcc
	v_cmp_gt_i32_e32 vcc, v99, v60
	v_cmp_ge_i32_e64 s[0:1], v60, v112
	s_and_b64 s[0:1], vcc, s[0:1]
	s_and_b64 vcc, s[0:1], s[10:11]
	v_cndmask_b32_e32 v99, v93, v111, vcc
	ds_read_b128 v[108:111], v95 offset:18432
	ds_read_b128 v[112:115], v95 offset:18496
	s_waitcnt lgkmcnt(1)
	v_mfma_f32_16x16x32_bf16 v[12:15], v[12:15], v[108:111], 0
	v_add_u32_e32 v124, 0x80, v30
	v_cmp_gt_i32_e32 vcc, v124, v31
	v_cmp_ge_i32_e64 s[0:1], v31, v30
	s_waitcnt lgkmcnt(0)
; __device__ __forceinline__ float row16_sum(float v) { v += dpp_perm<0xB1, 0xF>(v); v += dpp_perm<0x4E, 0xF>(v); v += dpp_perm<0x141, 0xF>(v); v += dpp_perm<0x140, 0xF>(v); return v; }
; __device__ __forceinline__ float row16_max(float v) { v = fmaxf(v, dpp_perm<0xB1, 0xF>(v)); v = fmaxf(v, dpp_perm<0x4E, 0xF>(v)); v = fmaxf(v, dpp_perm<0x141, 0xF>(v)); v = fmaxf(v, dpp_perm<0x140, 0xF>(v)); return v; }
; __device__ __forceinline__ void attn_unit(const AtArgs& A, unsigned char* lds, int unit, int tid, int wave, int lane) {
;     ...
;         float m4[4], s4[4];
; #pragma unroll
;         for (int r = 0; r < 4; ++r) {
;             float m = sc[0][r];
; #pragma unroll
;             for (int kt = 1; kt < 9; ++kt) m = fmaxf(m, sc[kt][r]);
;             m = row16_max(m);
;             m4[r] = fmaxf(m, sink);
;             float s = 0.f;
; #pragma unroll
;             for (int kt = 0; kt < 9; ++kt) { const float e = __expf(sc[kt][r] - m4[r]); sc[kt][r] = e; s += e; }
;             s = row16_sum(s);
;             s4[r] = __builtin_amdgcn_rcpf(s + __expf(sink - m4[r]));
;         }
	v_mfma_f32_16x16x32_bf16 v[8:11], v[8:11], v[112:115], v[12:15]
	s_and_b64 vcc, vcc, s[0:1]
	v_cmp_ge_i32_e64 s[0:1], v58, v30
	v_add_u32_e32 v24, 0x900, v95
	v_mov_b32_e32 v95, 0
	v_mov_b32_e32 v108, 0
	s_nop 2
	v_cndmask_b32_e32 v8, v93, v8, vcc
	v_cmp_gt_i32_e32 vcc, v124, v58
	s_and_b64 vcc, vcc, s[0:1]
	v_cmp_ge_i32_e64 s[0:1], v59, v30
	v_cndmask_b32_e32 v58, v93, v9, vcc
	v_max3_f32 v9, v29, v96, v100
	v_cmp_gt_i32_e32 vcc, v124, v59
	v_max3_f32 v9, v9, v103, v116
	s_and_b64 vcc, vcc, s[0:1]
	v_max3_f32 v9, v9, v117, v119
	v_cndmask_b32_e32 v59, v93, v10, vcc
	v_max3_f32 v9, v9, v121, v8
	v_mov_b32_e32 v10, 0
	v_cmp_ge_i32_e64 s[0:1], v60, v30
	v_cmp_gt_i32_e32 vcc, v124, v60
	v_mov_b32_dpp v10, v9 quad_perm:[1,0,3,2] row_mask:0xf bank_mask:0xf
	v_max_f32_e32 v10, v10, v10
	v_max_f32_e32 v9, v9, v10
	v_mov_b32_e32 v10, 0
	s_and_b64 vcc, vcc, s[0:1]
	v_cndmask_b32_e32 v31, v93, v11, vcc
	v_mov_b32_dpp v10, v9 quad_perm:[2,3,0,1] row_mask:0xf bank_mask:0xf
	v_max_f32_e32 v10, v10, v10
	v_max_f32_e32 v9, v9, v10
	v_mov_b32_e32 v10, 0
	v_mov_b32_e32 v110, 0
	s_add_i32 s2, s2, 16
	v_mov_b32_dpp v10, v9 row_half_mirror row_mask:0xf bank_mask:0xf
	v_max_f32_e32 v10, v10, v10
	v_max_f32_e32 v9, v9, v10
	v_mov_b32_e32 v10, 0
	s_add_i32 s3, s3, 0xb000
	s_nop 0
	v_mov_b32_dpp v10, v9 row_mirror row_mask:0xf bank_mask:0xf
	v_max3_f32 v30, v9, v10, v38
	v_mul_f32_e32 v144, 0xbfb8aa3b, v30
	v_fmamk_f32 v10, v96, 0x3fb8aa3b, v144
	s_nop 0
	v_fmamk_f32 v9, v29, 0x3fb8aa3b, v144
	v_exp_f32_e32 v29, v10
	v_fmamk_f32 v10, v100, 0x3fb8aa3b, v144
	s_nop 0
	s_nop 0
	v_exp_f32_e32 v14, v9
	v_exp_f32_e32 v15, v10
	v_fmamk_f32 v10, v103, 0x3fb8aa3b, v144
	s_nop 0
	v_exp_f32_e32 v12, v10
	v_fmamk_f32 v10, v116, 0x3fb8aa3b, v144
	v_fmamk_f32 v11, v117, 0x3fb8aa3b, v144
	s_nop 0
	s_nop 0
	v_add_f32_e32 v9, 0, v14
	v_exp_f32_e32 v10, v10
	v_exp_f32_e32 v13, v11
	v_fmamk_f32 v11, v119, 0x3fb8aa3b, v144
	v_add_f32_e32 v9, v29, v9
	s_nop 0
	v_add_f32_e32 v9, v15, v9
	v_exp_f32_e32 v11, v11
	v_add_f32_e32 v9, v12, v9
	v_add_f32_e32 v9, v10, v9
	v_add_f32_e32 v9, v13, v9
	v_add_f32_e32 v60, v11, v9
	v_fmamk_f32 v9, v121, 0x3fb8aa3b, v144
	s_nop 0
	v_fmamk_f32 v8, v8, 0x3fb8aa3b, v144
	v_exp_f32_e32 v9, v9
	s_nop 0
	v_exp_f32_e32 v8, v8
	v_fmamk_f32 v30, v38, 0x3fb8aa3b, v144
	v_add_f32_e32 v60, v9, v60
	s_nop 0
	v_add_f32_e32 v60, v8, v60
	v_exp_f32_e32 v30, v30
	s_nop 0
	v_add_f32_dpp v60, v60, v60 quad_perm:[1,0,3,2] row_mask:0xf bank_mask:0xf bound_ctrl:1
	s_nop 1
	v_add_f32_dpp v60, v60, v60 quad_perm:[2,3,0,1] row_mask:0xf bank_mask:0xf bound_ctrl:1
	s_nop 1
	v_add_f32_dpp v60, v60, v60 row_half_mirror row_mask:0xf bank_mask:0xf bound_ctrl:1
	s_nop 1
	v_add_f32_dpp v60, v60, v60 row_mirror row_mask:0xf bank_mask:0xf bound_ctrl:1
	v_add_f32_e32 v30, v30, v60
	v_max3_f32 v60, v22, v26, v56
	v_max3_f32 v60, v60, v97, v101
	v_max3_f32 v60, v60, v118, v120
	v_max3_f32 v60, v60, v122, v58
	v_rcp_f32_e32 v30, v30
	s_nop 0
	v_mov_b32_dpp v95, v60 quad_perm:[1,0,3,2] row_mask:0xf bank_mask:0xf
	v_max_f32_e32 v95, v95, v95
	v_max_f32_e32 v60, v60, v95
	v_mov_b32_e32 v95, 0
	v_mul_f32_e32 v14, v14, v30
	v_mul_f32_e32 v10, v10, v30
	v_mov_b32_dpp v95, v60 quad_perm:[2,3,0,1] row_mask:0xf bank_mask:0xf
	v_max_f32_e32 v95, v95, v95
	v_max_f32_e32 v60, v60, v95
	v_mov_b32_e32 v95, 0
	v_cvt_pk_bf16_f32 v14, v14, s0
	v_cvt_pk_bf16_f32 v10, v10, s0
	v_mov_b32_dpp v95, v60 row_half_mirror row_mask:0xf bank_mask:0xf
	v_max_f32_e32 v95, v95, v95
	v_max_f32_e32 v60, v60, v95
	v_mov_b32_e32 v95, 0
	ds_write_b16 v79, v14
	ds_write_b16 v79, v10 offset:128
	v_mov_b32_dpp v95, v60 row_mirror row_mask:0xf bank_mask:0xf
	v_max3_f32 v60, v60, v95, v38
	v_mul_f32_e32 v145, 0xbfb8aa3b, v60
	v_fmamk_f32 v22, v22, 0x3fb8aa3b, v145
	s_nop 0
	v_fmamk_f32 v26, v26, 0x3fb8aa3b, v145
	v_exp_f32_e32 v22, v22
	s_nop 0
	v_fmamk_f32 v56, v56, 0x3fb8aa3b, v145
	v_exp_f32_e32 v26, v26
	s_nop 0
	v_fmamk_f32 v96, v97, 0x3fb8aa3b, v145
	v_exp_f32_e32 v56, v56
	s_nop 0
	v_fmamk_f32 v97, v101, 0x3fb8aa3b, v145
	v_exp_f32_e32 v96, v96
	s_nop 0
	v_fmamk_f32 v100, v118, 0x3fb8aa3b, v145
	v_add_f32_e32 v95, 0, v22
	v_exp_f32_e32 v97, v97
	s_nop 0
	v_fmamk_f32 v101, v120, 0x3fb8aa3b, v145
	v_add_f32_e32 v95, v26, v95
	v_exp_f32_e32 v100, v100
	s_nop 0
	v_fmamk_f32 v103, v122, 0x3fb8aa3b, v145
	v_add_f32_e32 v95, v56, v95
	v_exp_f32_e32 v101, v101
	s_nop 0
	v_fmamk_f32 v58, v58, 0x3fb8aa3b, v145
	v_add_f32_e32 v95, v96, v95
	v_exp_f32_e32 v103, v103
	s_nop 0
	v_add_f32_e32 v95, v97, v95
	v_exp_f32_e32 v58, v58
	v_add_f32_e32 v95, v100, v95
	v_add_f32_e32 v95, v101, v95
	v_add_f32_e32 v95, v103, v95
	v_fmamk_f32 v60, v38, 0x3fb8aa3b, v145
	v_add_f32_e32 v95, v58, v95
	s_nop 0
	v_exp_f32_e32 v60, v60
	v_add_f32_dpp v95, v95, v95 quad_perm:[1,0,3,2] row_mask:0xf bank_mask:0xf bound_ctrl:1
	v_mul_f32_e32 v12, v12, v30
	v_mul_f32_e32 v9, v9, v30
	v_add_f32_dpp v95, v95, v95 quad_perm:[2,3,0,1] row_mask:0xf bank_mask:0xf bound_ctrl:1
	v_mul_f32_e32 v8, v8, v30
	v_cvt_pk_bf16_f32 v12, v12, s0
	v_add_f32_dpp v95, v95, v95 row_half_mirror row_mask:0xf bank_mask:0xf bound_ctrl:1
	v_cvt_pk_bf16_f32 v9, v9, s0
	v_cvt_pk_bf16_f32 v8, v8, s0
	v_add_f32_dpp v95, v95, v95 row_mirror row_mask:0xf bank_mask:0xf bound_ctrl:1
	v_add_f32_e32 v60, v60, v95
	v_max3_f32 v95, v18, v20, v23
	v_max3_f32 v95, v95, v27, v57
	v_max3_f32 v95, v95, v98, v102
	v_max3_f32 v95, v95, v123, v59
	v_rcp_f32_e32 v60, v60
	ds_write_b16 v79, v12 offset:96
	v_mov_b32_dpp v108, v95 quad_perm:[1,0,3,2] row_mask:0xf bank_mask:0xf
	v_max_f32_e32 v108, v108, v108
	v_max_f32_e32 v95, v95, v108
	v_mov_b32_e32 v108, 0
	v_mul_f32_e32 v14, v22, v60
; __device__ __forceinline__ unsigned f2bf(float f) { return pk2(f, f) & 0xffffu; }
; __device__ __forceinline__ float row16_sum(float v) { v += dpp_perm<0xB1, 0xF>(v); v += dpp_perm<0x4E, 0xF>(v); v += dpp_perm<0x141, 0xF>(v); v += dpp_perm<0x140, 0xF>(v); return v; }
; __device__ __forceinline__ float row16_max(float v) { v = fmaxf(v, dpp_perm<0xB1, 0xF>(v)); v = fmaxf(v, dpp_perm<0x4E, 0xF>(v)); v = fmaxf(v, dpp_perm<0x141, 0xF>(v)); v = fmaxf(v, dpp_perm<0x140, 0xF>(v)); return v; }
; __device__ __forceinline__ void attn_unit(const AtArgs& A, unsigned char* lds, int unit, int tid, int wave, int lane) {
;     ...
;         float m4[4], s4[4];
; #pragma unroll
;         for (int r = 0; r < 4; ++r) {
;             float m = sc[0][r];
; #pragma unroll
;             for (int kt = 1; kt < 9; ++kt) m = fmaxf(m, sc[kt][r]);
;             m = row16_max(m);
;             m4[r] = fmaxf(m, sink);
;             float s = 0.f;
; #pragma unroll
;             for (int kt = 0; kt < 9; ++kt) { const float e = __expf(sc[kt][r] - m4[r]); sc[kt][r] = e; s += e; }
;             s = row16_sum(s);
;             s4[r] = __builtin_amdgcn_rcpf(s + __expf(sink - m4[r]));
;         }
; #pragma unroll
;         for (int kt = 0; kt < 9; ++kt)
; #pragma unroll
;             for (int r = 0; r < 4; ++r) PS[(fq * 4 + r) * PST + kt * 16 + fr] = (bf16)f2bf(sc[kt][r] * s4[r]);
	v_mul_f32_e32 v10, v97, v60
	v_mov_b32_dpp v108, v95 quad_perm:[2,3,0,1] row_mask:0xf bank_mask:0xf
	v_max_f32_e32 v108, v108, v108
	v_max_f32_e32 v95, v95, v108
	v_mov_b32_e32 v108, 0
	v_cvt_pk_bf16_f32 v14, v14, s0
	v_cvt_pk_bf16_f32 v10, v10, s0
	v_mov_b32_dpp v108, v95 row_half_mirror row_mask:0xf bank_mask:0xf
	v_max_f32_e32 v108, v108, v108
	v_max_f32_e32 v95, v95, v108
	v_mov_b32_e32 v108, 0
	ds_write_b16 v79, v14 offset:336
	ds_write_b16 v79, v10 offset:464
	v_mov_b32_dpp v108, v95 row_mirror row_mask:0xf bank_mask:0xf
	v_max3_f32 v95, v95, v108, v38
	v_mul_f32_e32 v146, 0xbfb8aa3b, v95
	v_fmamk_f32 v18, v18, 0x3fb8aa3b, v146
	s_nop 0
	v_fmamk_f32 v20, v20, 0x3fb8aa3b, v146
	v_exp_f32_e32 v18, v18
	s_nop 0
	v_fmamk_f32 v23, v23, 0x3fb8aa3b, v146
	v_exp_f32_e32 v20, v20
	s_nop 0
	v_fmamk_f32 v27, v27, 0x3fb8aa3b, v146
	v_exp_f32_e32 v23, v23
	s_nop 0
	v_fmamk_f32 v57, v57, 0x3fb8aa3b, v146
	v_exp_f32_e32 v27, v27
	s_nop 0
	v_fmamk_f32 v98, v98, 0x3fb8aa3b, v146
	v_add_f32_e32 v108, 0, v18
	v_exp_f32_e32 v57, v57
	s_nop 0
	v_fmamk_f32 v102, v102, 0x3fb8aa3b, v146
	v_add_f32_e32 v108, v20, v108
	v_exp_f32_e32 v98, v98
	s_nop 0
	v_fmamk_f32 v109, v123, 0x3fb8aa3b, v146
	v_add_f32_e32 v108, v23, v108
	v_exp_f32_e32 v102, v102
	s_nop 0
	v_fmamk_f32 v59, v59, 0x3fb8aa3b, v146
	v_add_f32_e32 v108, v27, v108
	v_exp_f32_e32 v109, v109
	s_nop 0
	v_add_f32_e32 v108, v57, v108
	v_exp_f32_e32 v59, v59
	v_add_f32_e32 v108, v98, v108
	v_add_f32_e32 v108, v102, v108
	v_add_f32_e32 v108, v109, v108
	v_fmamk_f32 v95, v38, 0x3fb8aa3b, v146
	v_add_f32_e32 v108, v59, v108
	s_nop 0
	v_exp_f32_e32 v95, v95
	v_add_f32_dpp v108, v108, v108 quad_perm:[1,0,3,2] row_mask:0xf bank_mask:0xf bound_ctrl:1
	v_mul_f32_e32 v12, v96, v60
	ds_write_b16 v79, v9 offset:224
	v_add_f32_dpp v108, v108, v108 quad_perm:[2,3,0,1] row_mask:0xf bank_mask:0xf bound_ctrl:1
	v_mul_f32_e32 v9, v103, v60
	ds_write_b16 v79, v8 offset:256
	v_add_f32_dpp v108, v108, v108 row_half_mirror row_mask:0xf bank_mask:0xf bound_ctrl:1
	v_mul_f32_e32 v8, v58, v60
	v_cvt_pk_bf16_f32 v12, v12, s0
	v_add_f32_dpp v108, v108, v108 row_mirror row_mask:0xf bank_mask:0xf bound_ctrl:1
	v_add_f32_e32 v95, v95, v108
	v_max3_f32 v108, v16, v17, v19
	v_max3_f32 v108, v108, v21, v25
	v_max3_f32 v108, v108, v28, v61
	v_max3_f32 v108, v108, v99, v31
	v_rcp_f32_e32 v95, v95
	v_cvt_pk_bf16_f32 v9, v9, s0
	v_mov_b32_dpp v110, v108 quad_perm:[1,0,3,2] row_mask:0xf bank_mask:0xf
	v_max_f32_e32 v110, v110, v110
	v_max_f32_e32 v108, v108, v110
	v_mov_b32_e32 v110, 0
	v_mul_f32_e32 v14, v18, v95
	v_mul_f32_e32 v10, v57, v95
	v_mov_b32_dpp v110, v108 quad_perm:[2,3,0,1] row_mask:0xf bank_mask:0xf
	v_max_f32_e32 v110, v110, v110
	v_max_f32_e32 v108, v108, v110
	v_mov_b32_e32 v110, 0
	v_cvt_pk_bf16_f32 v14, v14, s0
	v_cvt_pk_bf16_f32 v10, v10, s0
	v_mov_b32_dpp v110, v108 row_half_mirror row_mask:0xf bank_mask:0xf
	v_max_f32_e32 v110, v110, v110
	v_max_f32_e32 v108, v108, v110
	v_mov_b32_e32 v110, 0
	ds_write_b16 v79, v14 offset:672
	ds_write_b16 v79, v10 offset:800
	v_mov_b32_dpp v110, v108 row_mirror row_mask:0xf bank_mask:0xf
	v_max3_f32 v108, v108, v110, v38
	v_mul_f32_e32 v147, 0xbfb8aa3b, v108
	v_fmamk_f32 v16, v16, 0x3fb8aa3b, v147
	s_nop 0
	v_fmamk_f32 v17, v17, 0x3fb8aa3b, v147
	v_exp_f32_e32 v16, v16
	s_nop 0
	v_fmamk_f32 v19, v19, 0x3fb8aa3b, v147
	v_exp_f32_e32 v17, v17
	s_nop 0
	v_fmamk_f32 v21, v21, 0x3fb8aa3b, v147
	v_exp_f32_e32 v19, v19
	s_nop 0
	v_fmamk_f32 v25, v25, 0x3fb8aa3b, v147
	v_exp_f32_e32 v21, v21
	s_nop 0
	v_fmamk_f32 v28, v28, 0x3fb8aa3b, v147
	v_add_f32_e32 v110, 0, v16
	v_exp_f32_e32 v25, v25
	s_nop 0
	v_fmamk_f32 v61, v61, 0x3fb8aa3b, v147
	v_add_f32_e32 v110, v17, v110
	v_exp_f32_e32 v28, v28
	s_nop 0
	v_fmamk_f32 v99, v99, 0x3fb8aa3b, v147
	v_add_f32_e32 v110, v19, v110
	v_exp_f32_e32 v61, v61
	s_nop 0
	v_fmamk_f32 v31, v31, 0x3fb8aa3b, v147
	v_add_f32_e32 v110, v21, v110
	v_exp_f32_e32 v99, v99
	s_nop 0
	v_add_f32_e32 v110, v25, v110
	v_exp_f32_e32 v31, v31
	v_add_f32_e32 v110, v28, v110
	v_add_f32_e32 v110, v61, v110
	v_add_f32_e32 v110, v99, v110
	v_fmamk_f32 v108, v38, 0x3fb8aa3b, v147
	v_add_f32_e32 v110, v31, v110
	s_nop 0
	v_exp_f32_e32 v108, v108
	v_add_f32_dpp v110, v110, v110 quad_perm:[1,0,3,2] row_mask:0xf bank_mask:0xf bound_ctrl:1
	v_cvt_pk_bf16_f32 v8, v8, s0
	ds_write_b16 v79, v12 offset:432
	v_add_f32_dpp v110, v110, v110 quad_perm:[2,3,0,1] row_mask:0xf bank_mask:0xf bound_ctrl:1
	v_mul_f32_e32 v12, v27, v95
	ds_write_b16 v79, v9 offset:560
	v_add_f32_dpp v110, v110, v110 row_half_mirror row_mask:0xf bank_mask:0xf bound_ctrl:1
	v_mul_f32_e32 v9, v109, v95
	ds_write_b16 v79, v8 offset:592
	v_add_f32_dpp v110, v110, v110 row_mirror row_mask:0xf bank_mask:0xf bound_ctrl:1
	v_add_f32_e32 v108, v108, v110
	v_rcp_f32_e32 v108, v108
	v_mul_f32_e32 v8, v59, v95
	v_cvt_pk_bf16_f32 v12, v12, s0
	v_cvt_pk_bf16_f32 v9, v9, s0
	v_mul_f32_e32 v14, v16, v108
	v_mul_f32_e32 v10, v25, v108
	v_cvt_pk_bf16_f32 v14, v14, s0
	v_cvt_pk_bf16_f32 v10, v10, s0
	ds_write_b16 v79, v14 offset:1008
	v_mul_f32_e32 v14, v29, v30
	ds_write_b16 v79, v10 offset:1136
	v_mul_f32_e32 v10, v13, v30
	v_cvt_pk_bf16_f32 v14, v14, s0
	v_cvt_pk_bf16_f32 v10, v10, s0
	ds_write_b16 v79, v14 offset:32
	v_mul_f32_e32 v14, v26, v60
	ds_write_b16 v79, v10 offset:160
	v_mul_f32_e32 v10, v100, v60
	v_cvt_pk_bf16_f32 v14, v14, s0
	v_cvt_pk_bf16_f32 v10, v10, s0
	ds_write_b16 v79, v14 offset:368
	v_mul_f32_e32 v14, v20, v95
	ds_write_b16 v79, v10 offset:496
	v_mul_f32_e32 v10, v98, v95
	v_cvt_pk_bf16_f32 v14, v14, s0
	v_cvt_pk_bf16_f32 v10, v10, s0
	ds_write_b16 v79, v14 offset:704
	v_mul_f32_e32 v14, v17, v108
; __device__ __forceinline__ unsigned f2bf(float f) { return pk2(f, f) & 0xffffu; }
; #define LDS_WAIT() asm volatile("s_waitcnt lgkmcnt(0)" ::: "memory")
; __device__ __forceinline__ void attn_unit(const AtArgs& A, unsigned char* lds, int unit, int tid, int wave, int lane) {
;     ...
; #pragma unroll
;         for (int kt = 0; kt < 9; ++kt)
; #pragma unroll
;             for (int r = 0; r < 4; ++r) PS[(fq * 4 + r) * PST + kt * 16 + fr] = (bf16)f2bf(sc[kt][r] * s4[r]);
; #pragma unroll
;         for (int r = 0; r < 4; ++r) PS[(fq * 4 + r) * PST + 144 + fr] = 0;
;         LDS_WAIT();
;         f32x4 o[4];
; #pragma unroll
;         for (int dt = 0; dt < 4; ++dt) o[dt] = (f32x4){0.f, 0.f, 0.f, 0.f};
; #pragma unroll
;         for (int ks = 0; ks < 5; ++ks) {
;             const bf16x8 pa = *(const bf16x8*)(PS + fr * PST + ks * 32 + fq * 8);
; #pragma unroll
;             for (int dt = 0; dt < 4; ++dt) {
;                 const bf16x8 vb = *(const bf16x8*)(VT + (dt * 16 + fr) * VST + (((((q0 + ks * 32) >> 3) + fq) ^ ((dt * 2 + (fr >> 3)) & 7)) << 3));
;                 o[dt] = __builtin_amdgcn_mfma_f32_16x16x32_bf16(pa, vb, o[dt], 0, 0, 0);
;             }
;         }
	ds_write_b16 v79, v10 offset:832
	v_mul_f32_e32 v10, v28, v108
	v_cvt_pk_bf16_f32 v14, v14, s0
	v_cvt_pk_bf16_f32 v10, v10, s0
	ds_write_b16 v79, v14 offset:1040
	v_mul_f32_e32 v14, v15, v30
	ds_write_b16 v79, v10 offset:1168
	v_mul_f32_e32 v10, v11, v30
	v_cvt_pk_bf16_f32 v14, v14, s0
	v_cvt_pk_bf16_f32 v10, v10, s0
	ds_write_b16 v79, v14 offset:64
	v_mul_f32_e32 v14, v56, v60
	ds_write_b16 v79, v10 offset:192
	v_mul_f32_e32 v10, v101, v60
	v_cvt_pk_bf16_f32 v14, v14, s0
	v_cvt_pk_bf16_f32 v10, v10, s0
	ds_write_b16 v79, v14 offset:400
	v_mul_f32_e32 v14, v23, v95
	ds_write_b16 v79, v10 offset:528
	v_mul_f32_e32 v10, v102, v95
	v_cvt_pk_bf16_f32 v14, v14, s0
	v_cvt_pk_bf16_f32 v10, v10, s0
	v_cvt_pk_bf16_f32 v8, v8, s0
	ds_write_b16 v79, v14 offset:736
	v_mul_f32_e32 v14, v19, v108
	ds_write_b16 v79, v12 offset:768
	v_mul_f32_e32 v12, v21, v108
	ds_write_b16 v79, v10 offset:864
	v_mul_f32_e32 v10, v61, v108
	ds_write_b16 v79, v9 offset:896
	v_mul_f32_e32 v9, v99, v108
	ds_write_b16 v79, v8 offset:928
	v_mul_f32_e32 v8, v31, v108
	v_cvt_pk_bf16_f32 v14, v14, s0
	v_cvt_pk_bf16_f32 v12, v12, s0
	v_cvt_pk_bf16_f32 v10, v10, s0
	v_cvt_pk_bf16_f32 v9, v9, s0
	v_cvt_pk_bf16_f32 v8, v8, s0
	ds_write_b16 v79, v14 offset:1072
	ds_write_b16 v79, v12 offset:1104
	ds_write_b16 v79, v10 offset:1200
	ds_write_b16 v79, v9 offset:1232
	ds_write_b16 v79, v8 offset:1264
	ds_write_b16 v79, v39 offset:288
	ds_write_b16 v79, v39 offset:624
	ds_write_b16 v79, v39 offset:960
	ds_write_b16 v79, v39 offset:1296
	s_waitcnt lgkmcnt(0)
	ds_read_b128 v[8:11], v77
	v_add_u32_e32 v25, -8, v94
	v_xor_b32_e32 v12, v25, v78
	v_xor_b32_e32 v16, v25, v82
	v_xor_b32_e32 v20, v25, v83
	v_xor_b32_e32 v25, v25, v84
	v_lshl_add_u32 v12, v12, 4, v80
	v_lshl_add_u32 v16, v16, 4, v80
	v_lshl_add_u32 v20, v20, 4, v80
	v_lshl_add_u32 v25, v25, 4, v81
	ds_read_b128 v[12:15], v12 offset:36864
	ds_read_b128 v[16:19], v16 offset:47872
	ds_read_b128 v[20:23], v20 offset:58880
	ds_read_b128 v[26:29], v25 offset:33024
	v_add_u32_e32 v25, -4, v94
	v_xor_b32_e32 v30, v25, v78
	v_lshl_add_u32 v30, v30, 4, v80
	ds_read_b128 v[56:59], v30 offset:36864
	s_waitcnt lgkmcnt(4)
	v_mfma_f32_16x16x32_bf16 v[12:15], v[8:11], v[12:15], 0
	v_xor_b32_e32 v30, v25, v82
	v_lshl_add_u32 v30, v30, 4, v80
	v_mov_b32_e32 v95, v24
	s_waitcnt lgkmcnt(3)
	v_mfma_f32_16x16x32_bf16 v[16:19], v[8:11], v[16:19], 0
	s_waitcnt lgkmcnt(2)
	v_mfma_f32_16x16x32_bf16 v[20:23], v[8:11], v[20:23], 0
	s_waitcnt lgkmcnt(1)
	v_mfma_f32_16x16x32_bf16 v[8:11], v[8:11], v[26:29], 0
	ds_read_b128 v[26:29], v77 offset:64
	s_waitcnt lgkmcnt(0)
	v_mfma_f32_16x16x32_bf16 v[12:15], v[26:29], v[56:59], v[12:15]
	ds_read_b128 v[56:59], v30 offset:47872
	v_xor_b32_e32 v30, v25, v83
	v_lshl_add_u32 v30, v30, 4, v80
	s_waitcnt lgkmcnt(0)
	v_mfma_f32_16x16x32_bf16 v[16:19], v[26:29], v[56:59], v[16:19]
	ds_read_b128 v[56:59], v30 offset:58880
	v_xor_b32_e32 v25, v25, v84
	v_lshl_add_u32 v25, v25, 4, v81
	s_waitcnt lgkmcnt(0)
	v_mfma_f32_16x16x32_bf16 v[20:23], v[26:29], v[56:59], v[20:23]
	ds_read_b128 v[56:59], v25 offset:33024
	v_xor_b32_e32 v25, v94, v78
	v_lshl_add_u32 v25, v25, 4, v80
	s_waitcnt lgkmcnt(0)
	v_mfma_f32_16x16x32_bf16 v[8:11], v[26:29], v[56:59], v[8:11]
	ds_read_b128 v[26:29], v77 offset:128
	ds_read_b128 v[56:59], v25 offset:36864
	v_xor_b32_e32 v25, v94, v82
	v_lshl_add_u32 v25, v25, 4, v80
	s_waitcnt lgkmcnt(0)
	v_mfma_f32_16x16x32_bf16 v[12:15], v[26:29], v[56:59], v[12:15]
	ds_read_b128 v[56:59], v25 offset:47872
	v_xor_b32_e32 v25, v94, v83
	v_lshl_add_u32 v25, v25, 4, v80
	s_waitcnt lgkmcnt(0)
	v_mfma_f32_16x16x32_bf16 v[16:19], v[26:29], v[56:59], v[16:19]
	ds_read_b128 v[56:59], v25 offset:58880
	v_add_u32_e32 v25, 4, v94
	s_waitcnt lgkmcnt(0)
; __device__ __forceinline__ unsigned f2bf(float f) { return pk2(f, f) & 0xffffu; }
; #define LDS_WAIT() asm volatile("s_waitcnt lgkmcnt(0)" ::: "memory")
; __device__ __forceinline__ void attn_unit(const AtArgs& A, unsigned char* lds, int unit, int tid, int wave, int lane) {
;     ...
;             const u32x4 qc0 = qn0, qc1 = qn1;
;             { const bf16* pn = pq0 + (size_t)((st < 3) ? st + 1 : 3) * 16 * QW; qn0 = *(const u32x4*)pn; qn1 = *(const u32x4*)(pn + 8); }
;     ...
;         for (int ks = 0; ks < 5; ++ks) {
;             const bf16x8 pa = *(const bf16x8*)(PS + fr * PST + ks * 32 + fq * 8);
; #pragma unroll
;             for (int dt = 0; dt < 4; ++dt) {
;                 const bf16x8 vb = *(const bf16x8*)(VT + (dt * 16 + fr) * VST + (((((q0 + ks * 32) >> 3) + fq) ^ ((dt * 2 + (fr >> 3)) & 7)) << 3));
;                 o[dt] = __builtin_amdgcn_mfma_f32_16x16x32_bf16(pa, vb, o[dt], 0, 0, 0);
;             }
;         }
;         LDS_WAIT();
; #pragma unroll
;         for (int r = 0; r < 4; ++r)
; #pragma unroll
;             for (int dt = 0; dt < 4; ++dt) PS[(fq * 4 + r) * PST + dt * 16 + fr] = (bf16)f2bf(o[dt][r]);
;         LDS_WAIT();
; #pragma unroll
;         for (int j = 0; j < 2; ++j) {
;             const int tk = (lane >> 3) + 8 * j, c16 = lane & 7;
;             const size_t t = (size_t)b * SEQ + nb * 128 + q0 + tk;
;             *(u32x4*)(YB + t * 512 + hq * 64 + c16 * 8) = *(const u32x4*)(PS + tk * PST + c16 * 8);
;         }
;         LDS_WAIT();
;     }
	v_mfma_f32_16x16x32_bf16 v[56:59], v[26:29], v[56:59], v[20:23]
	s_nop 2
	v_xor_b32_e32 v20, v94, v84
	v_lshl_add_u32 v20, v20, 4, v81
	ds_read_b128 v[20:23], v20 offset:33024
	s_waitcnt lgkmcnt(0)
	v_mfma_f32_16x16x32_bf16 v[8:11], v[26:29], v[20:23], v[8:11]
	ds_read_b128 v[26:29], v77 offset:192
	v_xor_b32_e32 v20, v25, v78
	v_lshl_add_u32 v20, v20, 4, v80
	ds_read_b128 v[20:23], v20 offset:36864
	s_waitcnt lgkmcnt(0)
	v_mfma_f32_16x16x32_bf16 v[20:23], v[26:29], v[20:23], v[12:15]
	s_nop 2
	v_xor_b32_e32 v12, v25, v82
	v_lshl_add_u32 v12, v12, 4, v80
	ds_read_b128 v[12:15], v12 offset:47872
	s_waitcnt lgkmcnt(0)
	v_mfma_f32_16x16x32_bf16 v[16:19], v[26:29], v[12:15], v[16:19]
	v_xor_b32_e32 v12, v25, v83
	v_lshl_add_u32 v12, v12, 4, v80
	ds_read_b128 v[12:15], v12 offset:58880
	v_xor_b32_e32 v25, v25, v84
	v_lshl_add_u32 v25, v25, 4, v81
	s_waitcnt lgkmcnt(0)
	v_mfma_f32_16x16x32_bf16 v[12:15], v[26:29], v[12:15], v[56:59]
	s_nop 2
	ds_read_b128 v[56:59], v25 offset:33024
	v_add_u32_e32 v25, 8, v94
	s_waitcnt lgkmcnt(0)
	v_mfma_f32_16x16x32_bf16 v[8:11], v[26:29], v[56:59], v[8:11]
	ds_read_b128 v[26:29], v77 offset:256
	v_xor_b32_e32 v30, v25, v78
	v_lshl_add_u32 v30, v30, 4, v80
	ds_read_b128 v[56:59], v30 offset:36864
	v_xor_b32_e32 v30, v25, v82
	v_lshl_add_u32 v30, v30, 4, v80
	s_waitcnt lgkmcnt(0)
	v_mfma_f32_16x16x32_bf16 v[20:23], v[26:29], v[56:59], v[20:23]
	ds_read_b128 v[56:59], v30 offset:47872
	v_xor_b32_e32 v30, v25, v83
	v_lshl_add_u32 v30, v30, 4, v80
	s_waitcnt lgkmcnt(0)
	v_mfma_f32_16x16x32_bf16 v[16:19], v[26:29], v[56:59], v[16:19]
	ds_read_b128 v[56:59], v30 offset:58880
	v_xor_b32_e32 v25, v25, v84
	v_lshl_add_u32 v25, v25, 4, v81
	s_waitcnt lgkmcnt(0)
	v_mfma_f32_16x16x32_bf16 v[12:15], v[26:29], v[56:59], v[12:15]
	ds_read_b128 v[56:59], v25 offset:33024
	s_waitcnt lgkmcnt(0)
	v_cvt_pk_bf16_f32 v20, v20, s0
	s_waitcnt lgkmcnt(0)
	v_mfma_f32_16x16x32_bf16 v[8:11], v[26:29], v[56:59], v[8:11]
	v_cvt_pk_bf16_f32 v16, v16, s0
	s_nop 2
	v_cvt_pk_bf16_f32 v12, v12, s0
	ds_write_b16 v79, v20
	s_nop 1
	v_cvt_pk_bf16_f32 v8, v8, s0
	ds_write_b16 v79, v8 offset:96
	v_cvt_pk_bf16_f32 v8, v21, s0
	ds_write_b16 v79, v8 offset:336
	v_cvt_pk_bf16_f32 v8, v17, s0
	ds_write_b16 v79, v8 offset:368
	v_cvt_pk_bf16_f32 v8, v13, s0
	ds_write_b16 v79, v8 offset:400
	v_cvt_pk_bf16_f32 v8, v9, s0
	ds_write_b16 v79, v8 offset:432
	v_cvt_pk_bf16_f32 v8, v22, s0
	ds_write_b16 v79, v8 offset:672
	v_cvt_pk_bf16_f32 v8, v18, s0
	ds_write_b16 v79, v8 offset:704
	v_cvt_pk_bf16_f32 v8, v14, s0
	ds_write_b16 v79, v8 offset:736
	v_cvt_pk_bf16_f32 v8, v10, s0
	ds_write_b16 v79, v8 offset:768
	v_cvt_pk_bf16_f32 v8, v23, s0
	ds_write_b16 v79, v8 offset:1008
	v_cvt_pk_bf16_f32 v8, v19, s0
	ds_write_b16 v79, v8 offset:1040
	v_cvt_pk_bf16_f32 v8, v15, s0
	ds_write_b16 v79, v8 offset:1072
	v_cvt_pk_bf16_f32 v8, v11, s0
	ds_write_b16 v79, v16 offset:32
	ds_write_b16 v79, v12 offset:64
	ds_write_b16 v79, v8 offset:1104
	s_waitcnt lgkmcnt(0)
	ds_read_b128 v[8:11], v92
	v_lshl_add_u64 v[12:13], v[52:53], 0, s[20:21]
	s_mov_b32 s0, 0x1d800000
	v_add_co_u32_e32 v14, vcc, s0, v12
	s_mov_b32 s0, 0x1d802000
	s_nop 0
	v_addc_co_u32_e32 v15, vcc, 0, v13, vcc
	s_waitcnt lgkmcnt(0)
	global_store_dwordx4 v[14:15], v[8:11], off
	ds_read_b128 v[8:11], v92 offset:2688
	v_add_co_u32_e32 v12, vcc, s0, v12
	s_add_u32 s20, s20, 0x4000
	s_nop 0
	v_addc_co_u32_e32 v13, vcc, 0, v13, vcc
	s_waitcnt lgkmcnt(0)
	global_store_dwordx4 v[12:13], v[8:11], off
	s_waitcnt lgkmcnt(0)
	s_addc_u32 s21, s21, 0
	s_mov_b64 s[0:1], 0x400
	s_waitcnt vmcnt(2)
	v_mov_b64_e32 v[14:15], v[6:7]
	v_mov_b64_e32 v[10:11], v[2:3]
	v_add_u32_e32 v94, 2, v94
	v_lshl_add_u64 v[54:55], v[54:55], 0, s[0:1]
	s_cmp_lg_u32 s2, 64
	v_mov_b64_e32 v[12:13], v[4:5]
	v_mov_b64_e32 v[8:9], v[0:1]
	s_cbranch_scc0 .LBB0_492
